# baseline (speedup 1.0000x reference)
; __device__ __forceinline__ unsigned pk2(float lo, float hi) { unsigned r; asm("v_cvt_pk_bf16_f32 %0, %1, %2" : "=v"(r) : "v"(lo), "v"(hi)); return r; }
; __device__ __forceinline__ void st16_wt(void* p, u32x4 v) { asm volatile("global_store_dwordx4 %0, %1, off sc1\n\ts_nop 1" :: "v"(p), "v"(v) : "memory"); }
; #define PG8_BAR __builtin_amdgcn_s_barrier()
; template <class Epi, class Pre, bool AG = false>
; __device__ __forceinline__ void gemm_phase(LAS unsigned char* lds, const Gemm g, const StaticOrder& S, const Epi& E, const Pre& P) {
;     ...
;         if (wr == 0) PG8_BAR;
;     __device__ __forceinline__ void operator()(const AccT& acc, const pg8::Unit& u, int ui, int wr, int wc, int fr, int fq) const {
;         const int row0 = u.pm * 256 + wr * 64 + fr, col0 = u.pn * 128 + wc * 32 + 8 * fq;
;         float rs[2][4]; lane_rstd(lds, ui, wr, fr, rs);
; #pragma unroll
;         for (int ai = 0; ai < 2; ++ai)
; #pragma unroll
;             for (int m = 0; m < 4; ++m) {
;                 const float s = rs[ai][m]; u16* op = act + (size_t)(row0 + ai * 128 + m * 16) * FF + col0;
;                 const float c1 = -1.4426950408889634f * s, c2 = s * s;
;                 u32x4 w;
; #pragma unroll
;                 for (int n = 0; n < 2; ++n)
; #pragma unroll
;                     for (int hh = 0; hh < 2; ++hh) {
;                         const f32x2 ga = {acc[ai][0][m][n][2 * hh], acc[ai][0][m][n][2 * hh + 1]}, ua = {acc[ai][1][m][n][2 * hh], acc[ai][1][m][n][2 * hh + 1]};
;                         f32x2 t = ga * c1; t.x = fminf(t.x, 60.0f); t.y = fminf(t.y, 60.0f);
;                         f32x2 e; e.x = __builtin_amdgcn_exp2f(t.x); e.y = __builtin_amdgcn_exp2f(t.y);
;                         const f32x2 d = e + 1.0f;
;                         const float rp = __builtin_amdgcn_rcpf(d.x * d.y);
;                         const f32x2 r = {d.y * rp, d.x * rp};
;                         const f32x2 o = ((ga * ua) * c2) * r;
;                         w[2 * n + hh] = pk2(o.x, o.y);
;                     }
;                 st16_wt(op, w);
;             }
.Lpeel_gu_after:
	s_andn2_b64 vcc, s[10:11], s[6:7]
	s_and_b64 vcc, exec, vcc
	s_cbranch_vccz .LBB0_215
	s_barrier
.LBB0_215:
	v_and_b32_e32 v141, 15, v234
	s_lshl_b32 s12, s71, 8
	s_add_i32 s12, s12, s56
	v_or_b32_e32 v150, s12, v141
	s_lshl_b32 s12, s62, 7
	v_lshrrev_b32_e32 v140, 1, v234
	v_and_or_b32 v140, v140, 24, s12
	v_or_b32_e32 v152, s57, v140
	s_lshl_b32 s12, s70, 10
	s_add_i32 s12, s60, s12
	v_lshl_add_u32 v140, v141, 2, s12
	ds_read2_b32 v[194:195], v140 offset1:16
	ds_read2_b32 v[196:197], v140 offset0:32 offset1:48
	ds_read2_b32 v[198:199], v140 offset0:128 offset1:144
	ds_read2_b32 v[200:201], v140 offset0:160 offset1:176
	v_ashrrev_i32_e32 v153, 31, v152
	v_mov_b64_e32 v[142:143], s[8:9]
	v_mad_i64_i32 v[156:157], s[12:13], v150, s37, v[142:143]
	v_lshlrev_b64 v[152:153], 1, v[152:153]
	s_mov_b32 s12, 0xb0000
	s_mov_b32 s13, 0
	v_lshl_add_u64 v[156:157], v[156:157], 0, v[152:153]
	v_lshl_add_u64 v[154:155], v[156:157], 0, s[12:13]
	s_mov_b32 s12, 0x16000
	s_andn2_b64 vcc, exec, s[6:7]
	s_waitcnt lgkmcnt(0)
	v_mul_f32_e32 v158, 0xbfb8aa3b, v194
	v_mul_f32_e32 v161, v194, v194
	v_rcp_f32_e32 v160, v161
	v_pk_mul_f32 v[162:163], v[122:123], v[158:159] op_sel_hi:[1,0]
	v_pk_mul_f32 v[164:165], v[124:125], v[158:159] op_sel_hi:[1,0]
	v_pk_mul_f32 v[166:167], v[114:115], v[158:159] op_sel_hi:[1,0]
	v_pk_mul_f32 v[168:169], v[116:117], v[158:159] op_sel_hi:[1,0]
	v_exp_f32_e32 v162, v162
	v_exp_f32_e32 v163, v163
	v_exp_f32_e32 v164, v164
	v_exp_f32_e32 v165, v165
	v_exp_f32_e32 v166, v166
	v_exp_f32_e32 v167, v167
	v_exp_f32_e32 v168, v168
	v_exp_f32_e32 v169, v169
	v_pk_fma_f32 v[162:163], v[162:163], v[160:161], v[160:161] op_sel_hi:[1,0,0]
	v_pk_fma_f32 v[164:165], v[164:165], v[160:161], v[160:161] op_sel_hi:[1,0,0]
	v_pk_fma_f32 v[166:167], v[166:167], v[160:161], v[160:161] op_sel_hi:[1,0,0]
	v_pk_fma_f32 v[168:169], v[168:169], v[160:161], v[160:161] op_sel_hi:[1,0,0]
	v_pk_mul_f32 v[122:123], v[122:123], v[126:127]
	v_pk_mul_f32 v[124:125], v[124:125], v[128:129]
	v_pk_mul_f32 v[114:115], v[114:115], v[118:119]
	v_pk_mul_f32 v[116:117], v[116:117], v[120:121]
	v_rcp_f32_e32 v162, v162
	v_rcp_f32_e32 v163, v163
	v_rcp_f32_e32 v164, v164
	v_rcp_f32_e32 v165, v165
	v_rcp_f32_e32 v166, v166
	v_rcp_f32_e32 v167, v167
	v_rcp_f32_e32 v168, v168
	v_rcp_f32_e32 v169, v169
	s_nop 0
	v_pk_mul_f32 v[122:123], v[122:123], v[162:163]
	v_pk_mul_f32 v[124:125], v[124:125], v[164:165]
	v_pk_mul_f32 v[114:115], v[114:115], v[166:167]
	v_pk_mul_f32 v[116:117], v[116:117], v[168:169]
	v_cvt_pk_bf16_f32 v170, v122, v123
	v_cvt_pk_bf16_f32 v171, v124, v125
	v_cvt_pk_bf16_f32 v172, v114, v115
	v_cvt_pk_bf16_f32 v173, v116, v117
	global_store_dwordx4 v[156:157], v[170:173], off sc1
	s_nop 1
	v_lshl_add_u64 v[156:157], v[156:157], 0, s[12:13]
	v_mul_f32_e32 v158, 0xbfb8aa3b, v195
	v_mul_f32_e32 v161, v195, v195
	v_rcp_f32_e32 v160, v161
	v_pk_mul_f32 v[162:163], v[106:107], v[158:159] op_sel_hi:[1,0]
	v_pk_mul_f32 v[164:165], v[108:109], v[158:159] op_sel_hi:[1,0]
	v_pk_mul_f32 v[166:167], v[98:99], v[158:159] op_sel_hi:[1,0]
	v_pk_mul_f32 v[168:169], v[100:101], v[158:159] op_sel_hi:[1,0]
	v_exp_f32_e32 v162, v162
	v_exp_f32_e32 v163, v163
	v_exp_f32_e32 v164, v164
	v_exp_f32_e32 v165, v165
	v_exp_f32_e32 v166, v166
	v_exp_f32_e32 v167, v167
	v_exp_f32_e32 v168, v168
	v_exp_f32_e32 v169, v169
	v_pk_fma_f32 v[162:163], v[162:163], v[160:161], v[160:161] op_sel_hi:[1,0,0]
	v_pk_fma_f32 v[164:165], v[164:165], v[160:161], v[160:161] op_sel_hi:[1,0,0]
	v_pk_fma_f32 v[166:167], v[166:167], v[160:161], v[160:161] op_sel_hi:[1,0,0]
	v_pk_fma_f32 v[168:169], v[168:169], v[160:161], v[160:161] op_sel_hi:[1,0,0]
	v_pk_mul_f32 v[106:107], v[106:107], v[110:111]
	v_pk_mul_f32 v[108:109], v[108:109], v[112:113]
	v_pk_mul_f32 v[98:99], v[98:99], v[102:103]
	v_pk_mul_f32 v[100:101], v[100:101], v[104:105]
	v_rcp_f32_e32 v162, v162
	v_rcp_f32_e32 v163, v163
	v_rcp_f32_e32 v164, v164
	v_rcp_f32_e32 v165, v165
	v_rcp_f32_e32 v166, v166
	v_rcp_f32_e32 v167, v167
	v_rcp_f32_e32 v168, v168
	v_rcp_f32_e32 v169, v169
	s_nop 0
	v_pk_mul_f32 v[106:107], v[106:107], v[162:163]
	v_pk_mul_f32 v[108:109], v[108:109], v[164:165]
	v_pk_mul_f32 v[98:99], v[98:99], v[166:167]
	v_pk_mul_f32 v[100:101], v[100:101], v[168:169]
	v_cvt_pk_bf16_f32 v174, v106, v107
	v_cvt_pk_bf16_f32 v175, v108, v109
	v_cvt_pk_bf16_f32 v176, v98, v99
	v_cvt_pk_bf16_f32 v177, v100, v101
	global_store_dwordx4 v[156:157], v[174:177], off sc1
	s_nop 1
	v_lshl_add_u64 v[156:157], v[156:157], 0, s[12:13]
	v_mul_f32_e32 v158, 0xbfb8aa3b, v196
	v_mul_f32_e32 v161, v196, v196
	v_rcp_f32_e32 v160, v161
	v_pk_mul_f32 v[162:163], v[90:91], v[158:159] op_sel_hi:[1,0]
	v_pk_mul_f32 v[164:165], v[92:93], v[158:159] op_sel_hi:[1,0]
	v_pk_mul_f32 v[166:167], v[82:83], v[158:159] op_sel_hi:[1,0]
	v_pk_mul_f32 v[168:169], v[84:85], v[158:159] op_sel_hi:[1,0]
	v_exp_f32_e32 v162, v162
	v_exp_f32_e32 v163, v163
	v_exp_f32_e32 v164, v164
	v_exp_f32_e32 v165, v165
	v_exp_f32_e32 v166, v166
	v_exp_f32_e32 v167, v167
	v_exp_f32_e32 v168, v168
	v_exp_f32_e32 v169, v169
	v_pk_fma_f32 v[162:163], v[162:163], v[160:161], v[160:161] op_sel_hi:[1,0,0]
	v_pk_fma_f32 v[164:165], v[164:165], v[160:161], v[160:161] op_sel_hi:[1,0,0]
	v_pk_fma_f32 v[166:167], v[166:167], v[160:161], v[160:161] op_sel_hi:[1,0,0]
	v_pk_fma_f32 v[168:169], v[168:169], v[160:161], v[160:161] op_sel_hi:[1,0,0]
	v_pk_mul_f32 v[90:91], v[90:91], v[94:95]
	v_pk_mul_f32 v[92:93], v[92:93], v[96:97]
	v_pk_mul_f32 v[82:83], v[82:83], v[86:87]
	v_pk_mul_f32 v[84:85], v[84:85], v[88:89]
	v_rcp_f32_e32 v162, v162
	v_rcp_f32_e32 v163, v163
	v_rcp_f32_e32 v164, v164
; __device__ __forceinline__ unsigned pk2(float lo, float hi) { unsigned r; asm("v_cvt_pk_bf16_f32 %0, %1, %2" : "=v"(r) : "v"(lo), "v"(hi)); return r; }
; __device__ __forceinline__ void st16_wt(void* p, u32x4 v) { asm volatile("global_store_dwordx4 %0, %1, off sc1\n\ts_nop 1" :: "v"(p), "v"(v) : "memory"); }
;     __device__ __forceinline__ void operator()(const AccT& acc, const pg8::Unit& u, int ui, int wr, int wc, int fr, int fq) const {
;     ...
;                 const float s = rs[ai][m]; u16* op = act + (size_t)(row0 + ai * 128 + m * 16) * FF + col0;
;                 const float c1 = -1.4426950408889634f * s, c2 = s * s;
;                 u32x4 w;
; #pragma unroll
;                 for (int n = 0; n < 2; ++n)
; #pragma unroll
;                     for (int hh = 0; hh < 2; ++hh) {
;                         const f32x2 ga = {acc[ai][0][m][n][2 * hh], acc[ai][0][m][n][2 * hh + 1]}, ua = {acc[ai][1][m][n][2 * hh], acc[ai][1][m][n][2 * hh + 1]};
;                         f32x2 t = ga * c1; t.x = fminf(t.x, 60.0f); t.y = fminf(t.y, 60.0f);
;                         f32x2 e; e.x = __builtin_amdgcn_exp2f(t.x); e.y = __builtin_amdgcn_exp2f(t.y);
;                         const f32x2 d = e + 1.0f;
;                         const float rp = __builtin_amdgcn_rcpf(d.x * d.y);
;                         const f32x2 r = {d.y * rp, d.x * rp};
;                         const f32x2 o = ((ga * ua) * c2) * r;
;                         w[2 * n + hh] = pk2(o.x, o.y);
;                     }
;                 st16_wt(op, w);
	v_rcp_f32_e32 v165, v165
	v_rcp_f32_e32 v166, v166
	v_rcp_f32_e32 v167, v167
	v_rcp_f32_e32 v168, v168
	v_rcp_f32_e32 v169, v169
	s_nop 0
	v_pk_mul_f32 v[90:91], v[90:91], v[162:163]
	v_pk_mul_f32 v[92:93], v[92:93], v[164:165]
	v_pk_mul_f32 v[82:83], v[82:83], v[166:167]
	v_pk_mul_f32 v[84:85], v[84:85], v[168:169]
	v_cvt_pk_bf16_f32 v170, v90, v91
	v_cvt_pk_bf16_f32 v171, v92, v93
	v_cvt_pk_bf16_f32 v172, v82, v83
	v_cvt_pk_bf16_f32 v173, v84, v85
	global_store_dwordx4 v[156:157], v[170:173], off sc1
	s_nop 1
	v_lshl_add_u64 v[156:157], v[156:157], 0, s[12:13]
	v_mul_f32_e32 v158, 0xbfb8aa3b, v197
	v_mul_f32_e32 v161, v197, v197
	v_rcp_f32_e32 v160, v161
	v_pk_mul_f32 v[162:163], v[74:75], v[158:159] op_sel_hi:[1,0]
	v_pk_mul_f32 v[164:165], v[76:77], v[158:159] op_sel_hi:[1,0]
	v_pk_mul_f32 v[166:167], v[66:67], v[158:159] op_sel_hi:[1,0]
	v_pk_mul_f32 v[168:169], v[68:69], v[158:159] op_sel_hi:[1,0]
	v_exp_f32_e32 v162, v162
	v_exp_f32_e32 v163, v163
	v_exp_f32_e32 v164, v164
	v_exp_f32_e32 v165, v165
	v_exp_f32_e32 v166, v166
	v_exp_f32_e32 v167, v167
	v_exp_f32_e32 v168, v168
	v_exp_f32_e32 v169, v169
	v_pk_fma_f32 v[162:163], v[162:163], v[160:161], v[160:161] op_sel_hi:[1,0,0]
	v_pk_fma_f32 v[164:165], v[164:165], v[160:161], v[160:161] op_sel_hi:[1,0,0]
	v_pk_fma_f32 v[166:167], v[166:167], v[160:161], v[160:161] op_sel_hi:[1,0,0]
	v_pk_fma_f32 v[168:169], v[168:169], v[160:161], v[160:161] op_sel_hi:[1,0,0]
	v_pk_mul_f32 v[74:75], v[74:75], v[78:79]
	v_pk_mul_f32 v[76:77], v[76:77], v[80:81]
	v_pk_mul_f32 v[66:67], v[66:67], v[70:71]
	v_pk_mul_f32 v[68:69], v[68:69], v[72:73]
	v_rcp_f32_e32 v162, v162
	v_rcp_f32_e32 v163, v163
	v_rcp_f32_e32 v164, v164
	v_rcp_f32_e32 v165, v165
	v_rcp_f32_e32 v166, v166
	v_rcp_f32_e32 v167, v167
	v_rcp_f32_e32 v168, v168
	v_rcp_f32_e32 v169, v169
	s_nop 0
	v_pk_mul_f32 v[74:75], v[74:75], v[162:163]
	v_pk_mul_f32 v[76:77], v[76:77], v[164:165]
	v_pk_mul_f32 v[66:67], v[66:67], v[166:167]
	v_pk_mul_f32 v[68:69], v[68:69], v[168:169]
	v_cvt_pk_bf16_f32 v174, v74, v75
	v_cvt_pk_bf16_f32 v175, v76, v77
	v_cvt_pk_bf16_f32 v176, v66, v67
	v_cvt_pk_bf16_f32 v177, v68, v69
	global_store_dwordx4 v[156:157], v[174:177], off sc1
	s_nop 1
	v_mul_f32_e32 v158, 0xbfb8aa3b, v198
	v_mul_f32_e32 v161, v198, v198
	v_rcp_f32_e32 v160, v161
	v_pk_mul_f32 v[162:163], v[58:59], v[158:159] op_sel_hi:[1,0]
	v_pk_mul_f32 v[164:165], v[60:61], v[158:159] op_sel_hi:[1,0]
	v_pk_mul_f32 v[166:167], v[50:51], v[158:159] op_sel_hi:[1,0]
	v_pk_mul_f32 v[168:169], v[52:53], v[158:159] op_sel_hi:[1,0]
	v_exp_f32_e32 v162, v162
	v_exp_f32_e32 v163, v163
	v_exp_f32_e32 v164, v164
	v_exp_f32_e32 v165, v165
	v_exp_f32_e32 v166, v166
	v_exp_f32_e32 v167, v167
	v_exp_f32_e32 v168, v168
	v_exp_f32_e32 v169, v169
	v_pk_fma_f32 v[162:163], v[162:163], v[160:161], v[160:161] op_sel_hi:[1,0,0]
	v_pk_fma_f32 v[164:165], v[164:165], v[160:161], v[160:161] op_sel_hi:[1,0,0]
	v_pk_fma_f32 v[166:167], v[166:167], v[160:161], v[160:161] op_sel_hi:[1,0,0]
	v_pk_fma_f32 v[168:169], v[168:169], v[160:161], v[160:161] op_sel_hi:[1,0,0]
	v_pk_mul_f32 v[58:59], v[58:59], v[62:63]
	v_pk_mul_f32 v[60:61], v[60:61], v[64:65]
	v_pk_mul_f32 v[50:51], v[50:51], v[54:55]
	v_pk_mul_f32 v[52:53], v[52:53], v[56:57]
	v_rcp_f32_e32 v162, v162
	v_rcp_f32_e32 v163, v163
	v_rcp_f32_e32 v164, v164
	v_rcp_f32_e32 v165, v165
	v_rcp_f32_e32 v166, v166
	v_rcp_f32_e32 v167, v167
	v_rcp_f32_e32 v168, v168
	v_rcp_f32_e32 v169, v169
	s_nop 0
	v_pk_mul_f32 v[58:59], v[58:59], v[162:163]
	v_pk_mul_f32 v[60:61], v[60:61], v[164:165]
	v_pk_mul_f32 v[50:51], v[50:51], v[166:167]
	v_pk_mul_f32 v[52:53], v[52:53], v[168:169]
	v_cvt_pk_bf16_f32 v170, v58, v59
	v_cvt_pk_bf16_f32 v171, v60, v61
	v_cvt_pk_bf16_f32 v172, v50, v51
	v_cvt_pk_bf16_f32 v173, v52, v53
	global_store_dwordx4 v[154:155], v[170:173], off sc1
	s_nop 1
	v_lshl_add_u64 v[154:155], v[154:155], 0, s[12:13]
	v_mul_f32_e32 v158, 0xbfb8aa3b, v199
	v_mul_f32_e32 v161, v199, v199
	v_rcp_f32_e32 v160, v161
	v_pk_mul_f32 v[162:163], v[42:43], v[158:159] op_sel_hi:[1,0]
	v_pk_mul_f32 v[164:165], v[44:45], v[158:159] op_sel_hi:[1,0]
	v_pk_mul_f32 v[166:167], v[34:35], v[158:159] op_sel_hi:[1,0]
	v_pk_mul_f32 v[168:169], v[36:37], v[158:159] op_sel_hi:[1,0]
	v_exp_f32_e32 v162, v162
	v_exp_f32_e32 v163, v163
	v_exp_f32_e32 v164, v164
	v_exp_f32_e32 v165, v165
	v_exp_f32_e32 v166, v166
	v_exp_f32_e32 v167, v167
	v_exp_f32_e32 v168, v168
	v_exp_f32_e32 v169, v169
; __device__ __forceinline__ unsigned pk2(float lo, float hi) { unsigned r; asm("v_cvt_pk_bf16_f32 %0, %1, %2" : "=v"(r) : "v"(lo), "v"(hi)); return r; }
; __device__ __forceinline__ void st16_wt(void* p, u32x4 v) { asm volatile("global_store_dwordx4 %0, %1, off sc1\n\ts_nop 1" :: "v"(p), "v"(v) : "memory"); }
; #define PG8_BAR __builtin_amdgcn_s_barrier()
; template <class Epi, class Pre, bool AG = false>
; __device__ __forceinline__ void gemm_phase(LAS unsigned char* lds, const Gemm g, const StaticOrder& S, const Epi& E, const Pre& P) {
;     ...
;         if (!has_next) break;
; #pragma unroll
;         for (int a = 0; a < 2; ++a)
; #pragma unroll
;             for (int b = 0; b < 2; ++b)
; #pragma unroll
;                 for (int m = 0; m < 4; ++m)
; #pragma unroll
;                     for (int n = 0; n < 2; ++n) acc[a][b][m][n] = (f32x4){0.f, 0.f, 0.f, 0.f};
;         cur = nxt; cA = nA; cB = nB; ++ui;
;         if (wr == 1) PG8_BAR;
;     __device__ __forceinline__ void operator()(const AccT& acc, const pg8::Unit& u, int ui, int wr, int wc, int fr, int fq) const {
;     ...
;                 const float s = rs[ai][m]; u16* op = act + (size_t)(row0 + ai * 128 + m * 16) * FF + col0;
;                 const float c1 = -1.4426950408889634f * s, c2 = s * s;
;                 u32x4 w;
; #pragma unroll
;                 for (int n = 0; n < 2; ++n)
; #pragma unroll
;                     for (int hh = 0; hh < 2; ++hh) {
;                         const f32x2 ga = {acc[ai][0][m][n][2 * hh], acc[ai][0][m][n][2 * hh + 1]}, ua = {acc[ai][1][m][n][2 * hh], acc[ai][1][m][n][2 * hh + 1]};
;                         f32x2 t = ga * c1; t.x = fminf(t.x, 60.0f); t.y = fminf(t.y, 60.0f);
;                         f32x2 e; e.x = __builtin_amdgcn_exp2f(t.x); e.y = __builtin_amdgcn_exp2f(t.y);
;                         const f32x2 d = e + 1.0f;
;                         const float rp = __builtin_amdgcn_rcpf(d.x * d.y);
;                         const f32x2 r = {d.y * rp, d.x * rp};
;                         const f32x2 o = ((ga * ua) * c2) * r;
;                         w[2 * n + hh] = pk2(o.x, o.y);
;                     }
;                 st16_wt(op, w);
	v_pk_fma_f32 v[162:163], v[162:163], v[160:161], v[160:161] op_sel_hi:[1,0,0]
	v_pk_fma_f32 v[164:165], v[164:165], v[160:161], v[160:161] op_sel_hi:[1,0,0]
	v_pk_fma_f32 v[166:167], v[166:167], v[160:161], v[160:161] op_sel_hi:[1,0,0]
	v_pk_fma_f32 v[168:169], v[168:169], v[160:161], v[160:161] op_sel_hi:[1,0,0]
	v_pk_mul_f32 v[42:43], v[42:43], v[46:47]
	v_pk_mul_f32 v[44:45], v[44:45], v[48:49]
	v_pk_mul_f32 v[34:35], v[34:35], v[38:39]
	v_pk_mul_f32 v[36:37], v[36:37], v[40:41]
	v_rcp_f32_e32 v162, v162
	v_rcp_f32_e32 v163, v163
	v_rcp_f32_e32 v164, v164
	v_rcp_f32_e32 v165, v165
	v_rcp_f32_e32 v166, v166
	v_rcp_f32_e32 v167, v167
	v_rcp_f32_e32 v168, v168
	v_rcp_f32_e32 v169, v169
	s_nop 0
	v_pk_mul_f32 v[42:43], v[42:43], v[162:163]
	v_pk_mul_f32 v[44:45], v[44:45], v[164:165]
	v_pk_mul_f32 v[34:35], v[34:35], v[166:167]
	v_pk_mul_f32 v[36:37], v[36:37], v[168:169]
	v_cvt_pk_bf16_f32 v174, v42, v43
	v_cvt_pk_bf16_f32 v175, v44, v45
	v_cvt_pk_bf16_f32 v176, v34, v35
	v_cvt_pk_bf16_f32 v177, v36, v37
	global_store_dwordx4 v[154:155], v[174:177], off sc1
	s_nop 1
	v_lshl_add_u64 v[154:155], v[154:155], 0, s[12:13]
	v_mul_f32_e32 v158, 0xbfb8aa3b, v200
	v_mul_f32_e32 v161, v200, v200
	v_rcp_f32_e32 v160, v161
	v_pk_mul_f32 v[162:163], v[26:27], v[158:159] op_sel_hi:[1,0]
	v_pk_mul_f32 v[164:165], v[28:29], v[158:159] op_sel_hi:[1,0]
	v_pk_mul_f32 v[166:167], v[18:19], v[158:159] op_sel_hi:[1,0]
	v_pk_mul_f32 v[168:169], v[20:21], v[158:159] op_sel_hi:[1,0]
	v_exp_f32_e32 v162, v162
	v_exp_f32_e32 v163, v163
	v_exp_f32_e32 v164, v164
	v_exp_f32_e32 v165, v165
	v_exp_f32_e32 v166, v166
	v_exp_f32_e32 v167, v167
	v_exp_f32_e32 v168, v168
	v_exp_f32_e32 v169, v169
	v_pk_fma_f32 v[162:163], v[162:163], v[160:161], v[160:161] op_sel_hi:[1,0,0]
	v_pk_fma_f32 v[164:165], v[164:165], v[160:161], v[160:161] op_sel_hi:[1,0,0]
	v_pk_fma_f32 v[166:167], v[166:167], v[160:161], v[160:161] op_sel_hi:[1,0,0]
	v_pk_fma_f32 v[168:169], v[168:169], v[160:161], v[160:161] op_sel_hi:[1,0,0]
	v_pk_mul_f32 v[26:27], v[26:27], v[30:31]
	v_pk_mul_f32 v[28:29], v[28:29], v[32:33]
	v_pk_mul_f32 v[18:19], v[18:19], v[22:23]
	v_pk_mul_f32 v[20:21], v[20:21], v[24:25]
	v_rcp_f32_e32 v162, v162
	v_rcp_f32_e32 v163, v163
	v_rcp_f32_e32 v164, v164
	v_rcp_f32_e32 v165, v165
	v_rcp_f32_e32 v166, v166
	v_rcp_f32_e32 v167, v167
	v_rcp_f32_e32 v168, v168
	v_rcp_f32_e32 v169, v169
	s_nop 0
	v_pk_mul_f32 v[26:27], v[26:27], v[162:163]
	v_pk_mul_f32 v[28:29], v[28:29], v[164:165]
	v_pk_mul_f32 v[18:19], v[18:19], v[166:167]
	v_pk_mul_f32 v[20:21], v[20:21], v[168:169]
	v_cvt_pk_bf16_f32 v170, v26, v27
	v_cvt_pk_bf16_f32 v171, v28, v29
	v_cvt_pk_bf16_f32 v172, v18, v19
	v_cvt_pk_bf16_f32 v173, v20, v21
	global_store_dwordx4 v[154:155], v[170:173], off sc1
	s_nop 1
	v_lshl_add_u64 v[154:155], v[154:155], 0, s[12:13]
	v_mul_f32_e32 v158, 0xbfb8aa3b, v201
	v_mul_f32_e32 v161, v201, v201
	v_rcp_f32_e32 v160, v161
	v_pk_mul_f32 v[162:163], v[10:11], v[158:159] op_sel_hi:[1,0]
	v_pk_mul_f32 v[164:165], v[12:13], v[158:159] op_sel_hi:[1,0]
	v_pk_mul_f32 v[166:167], v[6:7], v[158:159] op_sel_hi:[1,0]
	v_pk_mul_f32 v[168:169], v[8:9], v[158:159] op_sel_hi:[1,0]
	v_exp_f32_e32 v162, v162
	v_exp_f32_e32 v163, v163
	v_exp_f32_e32 v164, v164
	v_exp_f32_e32 v165, v165
	v_exp_f32_e32 v166, v166
	v_exp_f32_e32 v167, v167
	v_exp_f32_e32 v168, v168
	v_exp_f32_e32 v169, v169
	v_pk_fma_f32 v[162:163], v[162:163], v[160:161], v[160:161] op_sel_hi:[1,0,0]
	v_pk_fma_f32 v[164:165], v[164:165], v[160:161], v[160:161] op_sel_hi:[1,0,0]
	v_pk_fma_f32 v[166:167], v[166:167], v[160:161], v[160:161] op_sel_hi:[1,0,0]
	v_pk_fma_f32 v[168:169], v[168:169], v[160:161], v[160:161] op_sel_hi:[1,0,0]
	v_pk_mul_f32 v[10:11], v[10:11], v[14:15]
	v_pk_mul_f32 v[12:13], v[12:13], v[16:17]
	v_pk_mul_f32 v[6:7], v[6:7], v[2:3]
	v_pk_mul_f32 v[8:9], v[8:9], v[4:5]
	v_rcp_f32_e32 v162, v162
	v_rcp_f32_e32 v163, v163
	v_rcp_f32_e32 v164, v164
	v_rcp_f32_e32 v165, v165
	v_rcp_f32_e32 v166, v166
	v_rcp_f32_e32 v167, v167
	v_rcp_f32_e32 v168, v168
	v_rcp_f32_e32 v169, v169
	s_nop 0
	v_pk_mul_f32 v[10:11], v[10:11], v[162:163]
	v_pk_mul_f32 v[12:13], v[12:13], v[164:165]
	v_pk_mul_f32 v[6:7], v[6:7], v[166:167]
	v_pk_mul_f32 v[8:9], v[8:9], v[168:169]
	v_cvt_pk_bf16_f32 v174, v10, v11
	v_cvt_pk_bf16_f32 v175, v12, v13
	v_cvt_pk_bf16_f32 v176, v6, v7
	v_cvt_pk_bf16_f32 v177, v8, v9
	global_store_dwordx4 v[154:155], v[174:177], off sc1
	s_nop 1
	s_nop 1
	s_mov_b64 s[12:13], -1
	s_cbranch_vccnz .LBB0_208
	s_branch .LBB0_207
